# attention QK block: map-0 Q fragments kept in registers (VGPR 256), mask-free copy for tiles below the diagonal
# speedup vs baseline: 1.0248x; 1.0096x over previous
.LBB0_229:
	s_or_b64 exec, exec, s[0:1]
	s_waitcnt lgkmcnt(0)
	s_barrier
	ds_read_b32 v0, v181
	s_mov_b64 s[0:1], -1
	s_waitcnt lgkmcnt(0)
	v_cmp_lt_i32_e32 vcc, s25, v0
	v_readfirstlane_b32 s4, v0
	s_cbranch_vccnz .LBB0_224
	s_ashr_i32 s0, s4, 31
	s_lshr_b32 s0, s0, 23
	s_add_i32 s0, s4, s0
	s_and_b32 s0, s0, 0xfffffe00
	s_sub_i32 s6, s4, s0
	v_readfirstlane_b32 s0, v183
	s_ashr_i32 s7, s6, 5
	s_lshr_b32 s0, s0, 2
	s_sub_i32 s8, 15, s7
	s_and_b32 s9, s0, 0x3ffffff0
	s_lshl_b32 s0, s6, 8
	s_and_b32 s4, s6, 7
	s_lshl_b32 s5, s8, 7
	s_and_b32 s16, s0, 0x1800
	s_add_i32 s37, s9, s5
	s_add_i32 s10, s4, 1
	s_mul_i32 s0, s16, 0xc000
	s_add_u32 s0, s74, s0
	s_addc_u32 s1, s75, 0
	s_lshl_b32 s36, s4, 8
	s_mul_i32 s11, s8, 0x600000
	s_mul_hi_u32 s5, s5, 0xc000
	s_add_u32 s11, s0, s11
	s_addc_u32 s5, s1, s5
	s_lshl_b32 s4, s4, 9
	s_add_u32 s4, s11, s4
	s_addc_u32 s5, s5, 0
	v_mov_b32_e32 v149, v145
	v_lshl_add_u64 v[0:1], s[4:5], 0, v[148:149]
	v_lshl_add_u64 v[28:29], v[0:1], 0, s[18:19]
	v_mov_b32_e32 v151, v145
	v_lshl_add_u64 v[24:25], v[28:29], 0, v[150:151]
	v_add_co_u32_e32 v8, vcc, s27, v24
	v_mov_b32_e32 v153, v145
	s_nop 0
	v_addc_co_u32_e32 v9, vcc, 0, v25, vcc
	v_add_co_u32_e32 v16, vcc, s28, v24
	v_or_b32_e32 v33, s36, v174
	s_waitcnt lgkmcnt(0)
	s_barrier
	v_lshl_add_u64 v[4:5], v[28:29], 0, v[152:153]
	v_addc_co_u32_e32 v17, vcc, 0, v25, vcc
	global_load_dwordx4 v[0:3], v[24:25], off
	s_nop 0
	global_load_dwordx4 v[4:7], v[4:5], off
	v_add_co_u32_e32 v24, vcc, s29, v24
	v_lshlrev_b32_e32 v162, 1, v33
	v_mov_b32_e32 v163, v145
	v_or_b32_e32 v32, s36, v173
	v_mov_b32_e32 v155, v145
	v_mov_b32_e32 v157, v145
	v_addc_co_u32_e32 v25, vcc, 0, v25, vcc
	v_mov_b32_e32 v159, v145
	v_lshl_add_u64 v[48:49], s[0:1], 0, v[162:163]
	v_lshl_add_u64 v[12:13], v[28:29], 0, v[154:155]
	v_lshl_add_u64 v[20:21], v[28:29], 0, v[156:157]
	v_lshl_add_u64 v[28:29], v[28:29], 0, v[158:159]
	v_lshlrev_b32_e32 v144, 1, v32
	v_add_co_u32_e32 v44, vcc, s30, v48
	global_load_dwordx4 v[8:11], v[8:9], off
	s_nop 0
	global_load_dwordx4 v[12:15], v[12:13], off
	s_nop 0
	global_load_dwordx4 v[16:19], v[16:17], off
	s_nop 0
	global_load_dwordx4 v[20:23], v[20:21], off
	v_addc_co_u32_e32 v45, vcc, 0, v49, vcc
	global_load_dwordx4 v[24:27], v[24:25], off
	v_lshl_add_u64 v[50:51], s[0:1], 0, v[144:145]
	global_load_dwordx4 v[28:31], v[28:29], off
	s_nop 0
	global_load_dwordx4 v[32:35], v144, s[0:1]
	global_load_dwordx4 v[36:39], v144, s[0:1] offset:256
	s_lshl_b32 s38, s8, 2
	v_add_co_u32_e32 v50, vcc, s27, v50
	s_add_i32 s38, s38, 4
	global_load_dwordx4 v[40:43], v162, s[0:1]
	v_addc_co_u32_e32 v51, vcc, 0, v51, vcc
	global_load_dwordx4 v[44:47], v[44:45], off
	s_add_u32 s0, s0, 0x180000
	v_add_co_u32_e32 v48, vcc, s31, v48
	s_addc_u32 s1, s1, 0
	s_nop 0
	v_addc_co_u32_e32 v49, vcc, 0, v49, vcc
	global_load_dwordx4 v[116:119], v[50:51], off offset:256
	global_load_dwordx4 v[132:135], v[48:49], off
	global_load_dwordx4 v[124:127], v144, s[0:1]
	global_load_dwordx4 v[140:143], v162, s[0:1]
	v_cvt_f32_ubyte0_e32 v48, s10
	s_bfe_u32 s0, s6, 0x20003
	v_exp_f32_e64 v48, -v48
	s_or_b32 s41, s37, 15
	s_mul_i32 s0, s0, 0x6000000
	s_add_u32 s22, s70, s0
	s_addc_u32 s23, s71, 0
	s_lshl_b32 s0, s7, 2
	s_sub_i32 s42, s0, 64
	s_lshl_b32 s0, s7, 7
	v_mul_f32_e32 v149, 0x3fb8aa3b, v48
	s_mov_b32 s39, 31
	s_mov_b32 s40, 2
	v_mul_f32_e32 v151, 0x41800000, v149
	s_waitcnt vmcnt(15)
	ds_write_b128 v184, v[0:3]
	s_waitcnt vmcnt(14)
	ds_write_b128 v185, v[4:7]
	s_waitcnt vmcnt(13)
	ds_write_b128 v184, v[8:11] offset:8704
	s_waitcnt vmcnt(12)
	ds_write_b128 v186, v[12:15]
	s_waitcnt vmcnt(11)
	ds_write_b128 v184, v[16:19] offset:17408
	s_waitcnt vmcnt(10)
	ds_write_b128 v187, v[20:23]
	s_waitcnt vmcnt(9)
	ds_write_b128 v184, v[24:27] offset:26112
	s_waitcnt vmcnt(8)
	ds_write_b128 v188, v[28:31]
	s_waitcnt vmcnt(7)
	ds_write_b128 v189, v[32:35]
	s_waitcnt vmcnt(6)
	ds_write_b128 v189, v[36:39] offset:8704
	s_waitcnt vmcnt(5)
	ds_write_b128 v190, v[40:43] offset:17408
	s_waitcnt vmcnt(4)
	ds_write_b128 v190, v[44:47] offset:26112
	v_or_b32_e32 v0, s9, v169
	s_waitcnt lgkmcnt(0)
	s_barrier
	v_mul_lo_u32 v0, v0, s3
	v_add_u32_e32 v1, s9, v180
	v_mov_b32_e32 v40, v145
	v_mov_b32_e32 v41, v145
	v_mov_b32_e32 v42, v145
	v_mov_b32_e32 v43, v145
	v_subrev_u32_e32 v194, s0, v1
	v_add_u32_e32 v195, v177, v0
	v_mov_b64_e32 v[58:59], v[42:43]
	v_mov_b64_e32 v[66:67], v[42:43]
	v_mov_b64_e32 v[74:75], v[42:43]
	v_mov_b64_e32 v[82:83], v[42:43]
	v_mov_b64_e32 v[90:91], v[42:43]
	v_mov_b64_e32 v[98:99], v[42:43]
	v_mov_b64_e32 v[106:107], v[42:43]
	v_mov_b64_e32 v[114:115], v[42:43]
	v_mov_b64_e32 v[130:131], v[42:43]
	v_mov_b64_e32 v[0:1], v[40:41]
	v_mov_b64_e32 v[4:5], v[40:41]
	v_mov_b64_e32 v[8:9], v[40:41]
	v_mov_b64_e32 v[16:17], v[40:41]
	v_mov_b64_e32 v[28:29], v[40:41]
	v_mov_b64_e32 v[46:47], v[42:43]
	v_mov_b64_e32 v[50:51], v[42:43]
	v_mov_b64_e32 v[62:63], v[42:43]
	v_mov_b64_e32 v[70:71], v[42:43]
	v_mov_b64_e32 v[78:79], v[42:43]
	v_mov_b64_e32 v[86:87], v[42:43]
	v_mov_b64_e32 v[94:95], v[42:43]
	v_mov_b64_e32 v[102:103], v[42:43]
	v_mov_b64_e32 v[110:111], v[42:43]
	v_mov_b64_e32 v[122:123], v[42:43]
	v_mov_b64_e32 v[138:139], v[42:43]
	v_mov_b64_e32 v[54:55], v[42:43]
	v_mov_b64_e32 v[36:37], v[40:41]
	v_mov_b64_e32 v[32:33], v[40:41]
	v_mov_b64_e32 v[24:25], v[40:41]
	v_mov_b64_e32 v[20:21], v[40:41]
	v_mov_b64_e32 v[12:13], v[40:41]
	v_mul_f32_e32 v153, 0, v149
	v_add_f32_e32 v155, v149, v149
	v_mul_f32_e32 v157, 0x40400000, v149
	v_mul_f32_e32 v159, 0x41880000, v149
	v_mul_f32_e32 v161, 0x41900000, v149
	v_mul_f32_e32 v193, 0x41980000, v149
	v_mov_b32_e32 v164, v145
	v_mov_b32_e32 v165, v145
	v_mov_b32_e32 v166, 0xf149f2ca
	v_mov_b64_e32 v[56:57], v[40:41]
	v_mov_b64_e32 v[64:65], v[40:41]
	v_mov_b64_e32 v[72:73], v[40:41]
	v_mov_b64_e32 v[80:81], v[40:41]
	v_mov_b64_e32 v[88:89], v[40:41]
	v_mov_b64_e32 v[96:97], v[40:41]
	v_mov_b64_e32 v[104:105], v[40:41]
	v_mov_b64_e32 v[112:113], v[40:41]
	v_mov_b64_e32 v[128:129], v[40:41]
	v_mov_b64_e32 v[2:3], v[42:43]
	v_mov_b64_e32 v[6:7], v[42:43]
	v_mov_b64_e32 v[10:11], v[42:43]
	v_mov_b64_e32 v[18:19], v[42:43]
	v_mov_b64_e32 v[30:31], v[42:43]
	v_mov_b64_e32 v[44:45], v[40:41]
	v_mov_b64_e32 v[48:49], v[40:41]
	v_mov_b64_e32 v[60:61], v[40:41]
	v_mov_b64_e32 v[68:69], v[40:41]
	v_mov_b64_e32 v[76:77], v[40:41]
	v_mov_b64_e32 v[84:85], v[40:41]
	v_mov_b64_e32 v[92:93], v[40:41]
	v_mov_b64_e32 v[100:101], v[40:41]
	v_mov_b64_e32 v[108:109], v[40:41]
	v_mov_b64_e32 v[120:121], v[40:41]
	v_mov_b64_e32 v[136:137], v[40:41]
	v_mov_b32_e32 v167, 0xf149f2ca
	v_mov_b64_e32 v[52:53], v[40:41]
	v_mov_b64_e32 v[38:39], v[42:43]
	v_mov_b64_e32 v[34:35], v[42:43]
	v_mov_b64_e32 v[26:27], v[42:43]
	v_mov_b64_e32 v[22:23], v[42:43]
	v_mov_b64_e32 v[14:15], v[42:43]
	ds_read_b128 v[240:243], v195
	ds_read_b128 v[244:247], v195 offset:64
	ds_read_b128 v[248:251], v195 offset:128
	ds_read_b128 v[252:255], v195 offset:192
	s_waitcnt lgkmcnt(0)

.Latt_top_done:
	s_sub_i32 s0, s39, 31
	s_cmp_gt_u32 s0, s41
	s_cbranch_scc1 .LBB0_235
	s_cmp_gt_u32 s39, s37
	s_cbranch_scc1 .Latt_diag
	v_add_u32_e32 v168, s43, v178
	ds_read_b128 v[196:199], v168
	ds_read_b128 v[208:211], v168 offset:64
	ds_read_b128 v[212:215], v168 offset:4352
	ds_read_b128 v[216:219], v168 offset:4416
	v_cvt_f32_i32_e32 v224, v194
	s_waitcnt lgkmcnt(3)
	v_mfma_f32_16x16x32_bf16 v[196:199], v[196:199], v[240:243], 0
	s_waitcnt lgkmcnt(1)
	v_mfma_f32_16x16x32_bf16 v[200:203], v[212:215], v[240:243], 0
	ds_read_b128 v[212:215], v168 offset:128
	v_mfma_f32_16x16x32_bf16 v[196:199], v[208:211], v[244:247], v[196:199]
	ds_read_b128 v[220:223], v168 offset:192
	s_waitcnt lgkmcnt(2)
	v_mfma_f32_16x16x32_bf16 v[200:203], v[216:219], v[244:247], v[200:203]
	ds_read_b128 v[216:219], v168 offset:4480
	s_waitcnt lgkmcnt(2)
	v_mfma_f32_16x16x32_bf16 v[196:199], v[212:215], v[248:251], v[196:199]
	ds_read_b128 v[212:215], v168 offset:4544
	s_waitcnt lgkmcnt(1)
	v_mfma_f32_16x16x32_bf16 v[200:203], v[216:219], v[248:251], v[200:203]
	v_mfma_f32_16x16x32_bf16 v[220:223], v[220:223], v[252:255], v[196:199]
	s_waitcnt lgkmcnt(0)
	v_mfma_f32_16x16x32_bf16 v[202:205], v[212:215], v[252:255], v[200:203]
	ds_read_b128 v[206:209], v168 offset:8704
	ds_read_b128 v[210:213], v195 offset:34816
	ds_read_b128 v[214:217], v168 offset:13056
	v_mul_f32_e64 v197, -v149, v224
	s_nop 1
	v_fmamk_f32 v196, v220, 0x3e0293ee, v197
	v_add_f32_e32 v198, v153, v196
	v_fmamk_f32 v196, v221, 0x3e0293ee, v197
	v_fmamk_f32 v200, v222, 0x3e0293ee, v197
	v_fmamk_f32 v201, v223, 0x3e0293ee, v197
	ds_read_b128 v[218:221], v195 offset:34880
	ds_read_b128 v[222:225], v168 offset:8768
	s_waitcnt lgkmcnt(3)
	v_mfma_f32_16x16x32_bf16 v[206:209], v[206:209], v[210:213], 0
	ds_read_b128 v[226:229], v168 offset:13120
	v_add_f32_e32 v199, v149, v196
	s_waitcnt lgkmcnt(3)
	v_mfma_f32_16x16x32_bf16 v[210:213], v[214:217], v[210:213], 0
	ds_read_b128 v[214:217], v168 offset:8832
	v_add_f32_e32 v200, v155, v200
	v_add_f32_e32 v201, v157, v201
	s_waitcnt lgkmcnt(2)
	v_mfma_f32_16x16x32_bf16 v[206:209], v[222:225], v[218:221], v[206:209]
	ds_read_b128 v[222:225], v195 offset:34944
	ds_read_b128 v[230:233], v168 offset:13184
	v_fmamk_f32 v202, v202, 0x3e0293ee, v197
	v_fmamk_f32 v203, v203, 0x3e0293ee, v197
	v_max3_f32 v196, v198, s33, v199
	v_add_f32_e32 v202, v151, v202
	v_add_f32_e32 v203, v159, v203
	v_fmamk_f32 v204, v204, 0x3e0293ee, v197
	v_fmamk_f32 v205, v205, 0x3e0293ee, v197
	v_max3_f32 v196, v196, v200, v201
	v_add_f32_e32 v204, v161, v204
	v_add_f32_e32 v205, v193, v205
	s_waitcnt lgkmcnt(3)
	v_mfma_f32_16x16x32_bf16 v[210:213], v[226:229], v[218:221], v[210:213]
	ds_read_b128 v[218:221], v195 offset:35008
	ds_read_b128 v[226:229], v168 offset:8896
	v_max3_f32 v196, v196, v202, v203
	s_waitcnt lgkmcnt(3)
	v_mfma_f32_16x16x32_bf16 v[206:209], v[214:217], v[222:225], v[206:209]
	ds_read_b128 v[214:217], v168 offset:13248
	v_max3_f32 v196, v196, v204, v205
	v_mov_b32_e32 v234, v196
	s_nop 1
	v_permlane16_swap_b32_e32 v196, v234
	v_max_f32_e32 v234, v234, v234
	v_max_f32_e32 v196, v196, v196
	s_waitcnt lgkmcnt(3)
	v_mfma_f32_16x16x32_bf16 v[210:213], v[230:233], v[222:225], v[210:213]
	v_max_f32_e32 v196, v196, v234
	v_mov_b32_e32 v168, v196
	s_nop 1
	v_permlane32_swap_b32_e32 v196, v168
	s_waitcnt lgkmcnt(1)
	v_mfma_f32_16x16x32_bf16 v[206:209], v[226:229], v[218:221], v[206:209]
	v_max3_f32 v196, v167, v196, v168
	v_sub_f32_e32 v167, v167, v196
	v_exp_f32_e32 v167, v167
	s_waitcnt lgkmcnt(0)
	v_mfma_f32_16x16x32_bf16 v[210:213], v[214:217], v[218:221], v[210:213]
	s_nop 2
	v_fmamk_f32 v168, v206, 0x3e0293ee, v197
	v_add_f32_e32 v206, v153, v168
	v_fmamk_f32 v168, v207, 0x3e0293ee, v197
	v_add_f32_e32 v207, v149, v168
	v_fmamk_f32 v208, v208, 0x3e0293ee, v197
	v_fmamk_f32 v209, v209, 0x3e0293ee, v197
	v_add_f32_e32 v208, v155, v208
	v_add_f32_e32 v209, v157, v209
	v_fmamk_f32 v210, v210, 0x3e0293ee, v197
	v_fmamk_f32 v211, v211, 0x3e0293ee, v197
	v_max3_f32 v168, v206, s33, v207
	v_add_f32_e32 v210, v151, v210
	v_add_f32_e32 v211, v159, v211
	v_fmamk_f32 v212, v212, 0x3e0293ee, v197
	v_fmac_f32_e32 v197, 0x3e0293ee, v213
	v_max3_f32 v168, v168, v208, v209
	v_add_f32_e32 v212, v161, v212
	v_add_f32_e32 v213, v193, v197
	v_max3_f32 v168, v168, v210, v211
	v_max3_f32 v168, v168, v212, v213
	v_mov_b32_e32 v197, v168
	s_nop 1
	v_permlane16_swap_b32_e32 v168, v197
	v_max_f32_e32 v197, v197, v197
	v_max_f32_e32 v168, v168, v168
	v_max_f32_e32 v168, v168, v197
	v_mov_b32_e32 v197, v168
	s_nop 1
	v_permlane32_swap_b32_e32 v168, v197
	v_max3_f32 v197, v166, v168, v197
	v_sub_f32_e32 v166, v166, v197
	v_exp_f32_e32 v166, v166
	s_branch .Latt_s1done
.Latt_diag:
	v_add_u32_e32 v168, s43, v178
	ds_read_b128 v[196:199], v168
	ds_read_b128 v[208:211], v168 offset:64
	ds_read_b128 v[212:215], v168 offset:4352
	ds_read_b128 v[216:219], v168 offset:4416
	v_cvt_f32_i32_e32 v224, v194
	s_waitcnt lgkmcnt(3)
	v_mfma_f32_16x16x32_bf16 v[196:199], v[196:199], v[240:243], 0
	s_cmp_gt_u32 s39, s37
	v_cmp_gt_i32_e32 vcc, 0, v194
	s_cselect_b64 s[44:45], -1, 0
	s_waitcnt lgkmcnt(1)
	v_mfma_f32_16x16x32_bf16 v[200:203], v[212:215], v[240:243], 0
	ds_read_b128 v[212:215], v168 offset:128
	s_and_b64 vcc, s[44:45], vcc
	v_cmp_gt_i32_e64 s[4:5], 1, v194
	v_mfma_f32_16x16x32_bf16 v[196:199], v[208:211], v[244:247], v[196:199]
	ds_read_b128 v[220:223], v168 offset:192
	s_and_b64 s[4:5], s[44:45], s[4:5]
	v_cmp_gt_i32_e64 s[6:7], 2, v194
	s_waitcnt lgkmcnt(2)
	v_mfma_f32_16x16x32_bf16 v[200:203], v[216:219], v[244:247], v[200:203]
	ds_read_b128 v[216:219], v168 offset:4480
	v_cmp_gt_i32_e64 s[8:9], 3, v194
	v_cmp_gt_i32_e64 s[0:1], 16, v194
	s_waitcnt lgkmcnt(2)
	v_mfma_f32_16x16x32_bf16 v[196:199], v[212:215], v[248:251], v[196:199]
	ds_read_b128 v[212:215], v168 offset:4544
	s_and_b64 s[6:7], s[44:45], s[6:7]
	s_and_b64 s[8:9], s[44:45], s[8:9]
	s_waitcnt lgkmcnt(1)
	v_mfma_f32_16x16x32_bf16 v[200:203], v[216:219], v[248:251], v[200:203]
	v_cmp_gt_i32_e64 s[10:11], 17, v194
	s_and_b64 s[0:1], s[44:45], s[0:1]
	s_and_b64 s[10:11], s[44:45], s[10:11]
	v_mfma_f32_16x16x32_bf16 v[220:223], v[220:223], v[252:255], v[196:199]
	v_cmp_gt_i32_e64 s[12:13], 18, v194
	v_cmp_gt_i32_e64 s[14:15], 19, v194
	s_and_b64 s[12:13], s[44:45], s[12:13]
	s_waitcnt lgkmcnt(0)
	v_mfma_f32_16x16x32_bf16 v[202:205], v[212:215], v[252:255], v[200:203]
	ds_read_b128 v[206:209], v168 offset:8704
	ds_read_b128 v[210:213], v195 offset:34816
	ds_read_b128 v[214:217], v168 offset:13056
	v_mul_f32_e64 v197, -v149, v224
	v_fmamk_f32 v196, v220, 0x3e0293ee, v197
	v_add_f32_e32 v196, v153, v196
	v_cndmask_b32_e32 v198, v196, v192, vcc
	v_fmamk_f32 v196, v221, 0x3e0293ee, v197
	v_fmamk_f32 v200, v222, 0x3e0293ee, v197
	v_fmamk_f32 v201, v223, 0x3e0293ee, v197
	ds_read_b128 v[218:221], v195 offset:34880
	ds_read_b128 v[222:225], v168 offset:8768
	s_waitcnt lgkmcnt(3)
	v_mfma_f32_16x16x32_bf16 v[206:209], v[206:209], v[210:213], 0
	ds_read_b128 v[226:229], v168 offset:13120
	v_add_f32_e32 v196, v149, v196
	v_cndmask_b32_e64 v199, v196, v192, s[4:5]
	s_waitcnt lgkmcnt(3)
	v_mfma_f32_16x16x32_bf16 v[210:213], v[214:217], v[210:213], 0
	ds_read_b128 v[214:217], v168 offset:8832
	v_add_f32_e32 v200, v155, v200
	v_add_f32_e32 v201, v157, v201
	s_waitcnt lgkmcnt(2)
	v_mfma_f32_16x16x32_bf16 v[206:209], v[222:225], v[218:221], v[206:209]
	ds_read_b128 v[222:225], v195 offset:34944
	ds_read_b128 v[230:233], v168 offset:13184
	v_fmamk_f32 v202, v202, 0x3e0293ee, v197
	v_fmamk_f32 v203, v203, 0x3e0293ee, v197
	v_max3_f32 v196, v198, s33, v199
	v_cndmask_b32_e64 v200, v200, v192, s[6:7]
	v_cndmask_b32_e64 v201, v201, v192, s[8:9]
	v_add_f32_e32 v202, v151, v202
	v_add_f32_e32 v203, v159, v203
	v_fmamk_f32 v204, v204, 0x3e0293ee, v197
	v_fmamk_f32 v205, v205, 0x3e0293ee, v197
	v_max3_f32 v196, v196, v200, v201
	v_cndmask_b32_e64 v202, v202, v192, s[0:1]
	v_cndmask_b32_e64 v203, v203, v192, s[10:11]
	v_add_f32_e32 v204, v161, v204
	v_add_f32_e32 v205, v193, v205
	s_and_b64 s[14:15], s[44:45], s[14:15]
	s_waitcnt lgkmcnt(3)
	v_mfma_f32_16x16x32_bf16 v[210:213], v[226:229], v[218:221], v[210:213]
	ds_read_b128 v[218:221], v195 offset:35008
	ds_read_b128 v[226:229], v168 offset:8896
	v_max3_f32 v196, v196, v202, v203
	v_cndmask_b32_e64 v204, v204, v192, s[12:13]
	s_waitcnt lgkmcnt(3)
	v_mfma_f32_16x16x32_bf16 v[206:209], v[214:217], v[222:225], v[206:209]
	ds_read_b128 v[214:217], v168 offset:13248
	v_cndmask_b32_e64 v205, v205, v192, s[14:15]
	v_max3_f32 v196, v196, v204, v205
	v_mov_b32_e32 v234, v196
	s_nop 1
	v_permlane16_swap_b32_e32 v196, v234
	v_max_f32_e32 v234, v234, v234
	v_max_f32_e32 v196, v196, v196
	s_waitcnt lgkmcnt(3)
	v_mfma_f32_16x16x32_bf16 v[210:213], v[230:233], v[222:225], v[210:213]
	v_max_f32_e32 v196, v196, v234
	v_mov_b32_e32 v168, v196
	s_nop 1
	v_permlane32_swap_b32_e32 v196, v168
	s_waitcnt lgkmcnt(1)
	v_mfma_f32_16x16x32_bf16 v[206:209], v[226:229], v[218:221], v[206:209]
	v_max3_f32 v196, v167, v196, v168
	v_sub_f32_e32 v167, v167, v196
	v_exp_f32_e32 v167, v167
	s_waitcnt lgkmcnt(0)
	v_mfma_f32_16x16x32_bf16 v[210:213], v[214:217], v[218:221], v[210:213]
	s_nop 2
	v_fmamk_f32 v168, v206, 0x3e0293ee, v197
	v_add_f32_e32 v168, v153, v168
	v_cndmask_b32_e32 v206, v168, v192, vcc
	v_fmamk_f32 v168, v207, 0x3e0293ee, v197
	v_add_f32_e32 v168, v149, v168
	v_fmamk_f32 v208, v208, 0x3e0293ee, v197
	v_fmamk_f32 v209, v209, 0x3e0293ee, v197
	v_cndmask_b32_e64 v207, v168, v192, s[4:5]
	v_add_f32_e32 v208, v155, v208
	v_add_f32_e32 v209, v157, v209
	v_fmamk_f32 v210, v210, 0x3e0293ee, v197
	v_fmamk_f32 v211, v211, 0x3e0293ee, v197
	v_max3_f32 v168, v206, s33, v207
	v_cndmask_b32_e64 v208, v208, v192, s[6:7]
	v_cndmask_b32_e64 v209, v209, v192, s[8:9]
	v_add_f32_e32 v210, v151, v210
	v_add_f32_e32 v211, v159, v211
	v_fmamk_f32 v212, v212, 0x3e0293ee, v197
	v_fmac_f32_e32 v197, 0x3e0293ee, v213
	v_max3_f32 v168, v168, v208, v209
	v_cndmask_b32_e64 v210, v210, v192, s[0:1]
	v_cndmask_b32_e64 v211, v211, v192, s[10:11]
	v_add_f32_e32 v212, v161, v212
	v_add_f32_e32 v197, v193, v197
	v_max3_f32 v168, v168, v210, v211
	v_cndmask_b32_e64 v212, v212, v192, s[12:13]
	v_cndmask_b32_e64 v213, v197, v192, s[14:15]
	v_max3_f32 v168, v168, v212, v213
	v_mov_b32_e32 v197, v168
	s_nop 1
	v_permlane16_swap_b32_e32 v168, v197
	v_max_f32_e32 v197, v197, v197
	v_max_f32_e32 v168, v168, v168
	v_max_f32_e32 v168, v168, v197
	v_mov_b32_e32 v197, v168
	s_nop 1
	v_permlane32_swap_b32_e32 v168, v197
	v_max3_f32 v197, v166, v168, v197
	v_sub_f32_e32 v166, v166, v197
	v_exp_f32_e32 v166, v166
.Latt_s1done:
	v_cmp_neq_f32_e32 vcc, 1.0, v167
	v_cmp_neq_f32_e64 s[0:1], 1.0, v166
	s_or_b64 vcc, vcc, s[0:1]
	s_cbranch_vccz .LBB0_234
	v_mov_b32_e32 v168, v167
	v_pk_mul_f32 v[138:139], v[138:139], v[168:169] op_sel_hi:[1,0]
	v_pk_mul_f32 v[136:137], v[136:137], v[168:169] op_sel_hi:[1,0]
	v_pk_mul_f32 v[130:131], v[130:131], v[166:167] op_sel_hi:[1,0]
	v_pk_mul_f32 v[128:129], v[128:129], v[166:167] op_sel_hi:[1,0]
	v_pk_mul_f32 v[122:123], v[122:123], v[168:169] op_sel_hi:[1,0]
	v_pk_mul_f32 v[120:121], v[120:121], v[168:169] op_sel_hi:[1,0]
	v_pk_mul_f32 v[114:115], v[114:115], v[166:167] op_sel_hi:[1,0]
	v_pk_mul_f32 v[112:113], v[112:113], v[166:167] op_sel_hi:[1,0]
	v_pk_mul_f32 v[110:111], v[110:111], v[168:169] op_sel_hi:[1,0]
	v_pk_mul_f32 v[108:109], v[108:109], v[168:169] op_sel_hi:[1,0]
	v_pk_mul_f32 v[106:107], v[106:107], v[166:167] op_sel_hi:[1,0]
	v_pk_mul_f32 v[104:105], v[104:105], v[166:167] op_sel_hi:[1,0]
	v_pk_mul_f32 v[102:103], v[102:103], v[168:169] op_sel_hi:[1,0]
	v_pk_mul_f32 v[100:101], v[100:101], v[168:169] op_sel_hi:[1,0]
	v_pk_mul_f32 v[98:99], v[98:99], v[166:167] op_sel_hi:[1,0]
	v_pk_mul_f32 v[96:97], v[96:97], v[166:167] op_sel_hi:[1,0]
	v_pk_mul_f32 v[94:95], v[94:95], v[168:169] op_sel_hi:[1,0]
	v_pk_mul_f32 v[92:93], v[92:93], v[168:169] op_sel_hi:[1,0]
	v_pk_mul_f32 v[90:91], v[90:91], v[166:167] op_sel_hi:[1,0]
	v_pk_mul_f32 v[88:89], v[88:89], v[166:167] op_sel_hi:[1,0]
	v_pk_mul_f32 v[86:87], v[86:87], v[168:169] op_sel_hi:[1,0]
	v_pk_mul_f32 v[84:85], v[84:85], v[168:169] op_sel_hi:[1,0]
	v_pk_mul_f32 v[82:83], v[82:83], v[166:167] op_sel_hi:[1,0]
	v_pk_mul_f32 v[80:81], v[80:81], v[166:167] op_sel_hi:[1,0]
	v_pk_mul_f32 v[78:79], v[78:79], v[168:169] op_sel_hi:[1,0]
	v_pk_mul_f32 v[76:77], v[76:77], v[168:169] op_sel_hi:[1,0]
	v_pk_mul_f32 v[74:75], v[74:75], v[166:167] op_sel_hi:[1,0]
	v_pk_mul_f32 v[72:73], v[72:73], v[166:167] op_sel_hi:[1,0]
	v_pk_mul_f32 v[70:71], v[70:71], v[168:169] op_sel_hi:[1,0]
	v_pk_mul_f32 v[68:69], v[68:69], v[168:169] op_sel_hi:[1,0]
	v_pk_mul_f32 v[66:67], v[66:67], v[166:167] op_sel_hi:[1,0]
	v_pk_mul_f32 v[64:65], v[64:65], v[166:167] op_sel_hi:[1,0]
	v_pk_mul_f32 v[62:63], v[62:63], v[168:169] op_sel_hi:[1,0]
	v_pk_mul_f32 v[60:61], v[60:61], v[168:169] op_sel_hi:[1,0]
	v_pk_mul_f32 v[58:59], v[58:59], v[166:167] op_sel_hi:[1,0]
	v_pk_mul_f32 v[56:57], v[56:57], v[166:167] op_sel_hi:[1,0]
	v_pk_mul_f32 v[50:51], v[50:51], v[168:169] op_sel_hi:[1,0]
	v_pk_mul_f32 v[48:49], v[48:49], v[168:169] op_sel_hi:[1,0]
	v_pk_mul_f32 v[42:43], v[42:43], v[166:167] op_sel_hi:[1,0]
	v_pk_mul_f32 v[40:41], v[40:41], v[166:167] op_sel_hi:[1,0]
	v_pk_mul_f32 v[46:47], v[46:47], v[168:169] op_sel_hi:[1,0]
	v_pk_mul_f32 v[44:45], v[44:45], v[168:169] op_sel_hi:[1,0]
	v_pk_mul_f32 v[54:55], v[54:55], v[166:167] op_sel_hi:[1,0]
	v_pk_mul_f32 v[52:53], v[52:53], v[166:167] op_sel_hi:[1,0]
	v_pk_mul_f32 v[30:31], v[30:31], v[168:169] op_sel_hi:[1,0]
	v_pk_mul_f32 v[28:29], v[28:29], v[168:169] op_sel_hi:[1,0]
	v_pk_mul_f32 v[38:39], v[38:39], v[166:167] op_sel_hi:[1,0]
	v_pk_mul_f32 v[36:37], v[36:37], v[166:167] op_sel_hi:[1,0]
	v_pk_mul_f32 v[18:19], v[18:19], v[168:169] op_sel_hi:[1,0]
	v_pk_mul_f32 v[16:17], v[16:17], v[168:169] op_sel_hi:[1,0]
	v_pk_mul_f32 v[34:35], v[34:35], v[166:167] op_sel_hi:[1,0]
	v_pk_mul_f32 v[32:33], v[32:33], v[166:167] op_sel_hi:[1,0]
	v_pk_mul_f32 v[10:11], v[10:11], v[168:169] op_sel_hi:[1,0]
	v_pk_mul_f32 v[8:9], v[8:9], v[168:169] op_sel_hi:[1,0]
	v_pk_mul_f32 v[26:27], v[26:27], v[166:167] op_sel_hi:[1,0]
	v_pk_mul_f32 v[24:25], v[24:25], v[166:167] op_sel_hi:[1,0]
	v_pk_mul_f32 v[6:7], v[6:7], v[168:169] op_sel_hi:[1,0]
	v_pk_mul_f32 v[4:5], v[4:5], v[168:169] op_sel_hi:[1,0]
	v_pk_mul_f32 v[22:23], v[22:23], v[166:167] op_sel_hi:[1,0]
	v_pk_mul_f32 v[20:21], v[20:21], v[166:167] op_sel_hi:[1,0]
	v_pk_mul_f32 v[2:3], v[2:3], v[168:169] op_sel_hi:[1,0]
	v_pk_mul_f32 v[0:1], v[0:1], v[168:169] op_sel_hi:[1,0]
	v_pk_mul_f32 v[14:15], v[14:15], v[166:167] op_sel_hi:[1,0]
	v_pk_mul_f32 v[12:13], v[12:13], v[166:167] op_sel_hi:[1,0]

	.amdhsa_kernel _Z8mega_fwd4Args
		.amdhsa_group_segment_fixed_size 0
		.amdhsa_private_segment_fixed_size 0
		.amdhsa_kernarg_size 392
		.amdhsa_user_sgpr_count 2
		.amdhsa_user_sgpr_dispatch_ptr 0
		.amdhsa_user_sgpr_queue_ptr 0
		.amdhsa_user_sgpr_kernarg_segment_ptr 1
		.amdhsa_user_sgpr_dispatch_id 0
		.amdhsa_user_sgpr_kernarg_preload_length 0
		.amdhsa_user_sgpr_kernarg_preload_offset 0
		.amdhsa_user_sgpr_private_segment_size 0
		.amdhsa_uses_dynamic_stack 0
		.amdhsa_enable_private_segment 0
		.amdhsa_system_sgpr_workgroup_id_x 1
		.amdhsa_system_sgpr_workgroup_id_y 0
		.amdhsa_system_sgpr_workgroup_id_z 0
		.amdhsa_system_sgpr_workgroup_info 0
		.amdhsa_system_vgpr_workitem_id 2
		.amdhsa_next_free_vgpr 256
		.amdhsa_next_free_sgpr 100
		.amdhsa_accum_offset 256
		.amdhsa_reserve_vcc 1
		.amdhsa_float_round_mode_32 0
		.amdhsa_float_round_mode_16_64 0
		.amdhsa_float_denorm_mode_32 3
		.amdhsa_float_denorm_mode_16_64 3
		.amdhsa_dx10_clamp 1
		.amdhsa_ieee_mode 1
		.amdhsa_fp16_overflow 0
		.amdhsa_tg_split 0
		.amdhsa_exception_fp_ieee_invalid_op 0
		.amdhsa_exception_fp_denorm_src 0
		.amdhsa_exception_fp_ieee_div_zero 0
		.amdhsa_exception_fp_ieee_overflow 0
		.amdhsa_exception_fp_ieee_underflow 0
		.amdhsa_exception_fp_ieee_inexact 0
		.amdhsa_exception_int_div_zero 0
	.end_amdhsa_kernel

amdhsa.kernels:
  - .agpr_count:     0
    .args:
      - .offset:         0
        .size:           136
        .value_kind:     by_value
      - .offset:         136
        .size:           4
        .value_kind:     hidden_block_count_x
      - .offset:         140
        .size:           4
        .value_kind:     hidden_block_count_y
      - .offset:         144
        .size:           4
        .value_kind:     hidden_block_count_z
      - .offset:         148
        .size:           2
        .value_kind:     hidden_group_size_x
      - .offset:         150
        .size:           2
        .value_kind:     hidden_group_size_y
      - .offset:         152
        .size:           2
        .value_kind:     hidden_group_size_z
      - .offset:         154
        .size:           2
        .value_kind:     hidden_remainder_x
      - .offset:         156
        .size:           2
        .value_kind:     hidden_remainder_y
      - .offset:         158
        .size:           2
        .value_kind:     hidden_remainder_z
      - .offset:         176
        .size:           8
        .value_kind:     hidden_global_offset_x
      - .offset:         184
        .size:           8
        .value_kind:     hidden_global_offset_y
      - .offset:         192
        .size:           8
        .value_kind:     hidden_global_offset_z
      - .offset:         200
        .size:           2
        .value_kind:     hidden_grid_dims
      - .offset:         224
        .size:           8
        .value_kind:     hidden_multigrid_sync_arg
      - .offset:         256
        .size:           4
        .value_kind:     hidden_dynamic_lds_size
    .group_segment_fixed_size: 0
    .kernarg_segment_align: 8
    .kernarg_segment_size: 392
    .language:       OpenCL C
    .language_version:
      - 2
      - 0
    .max_flat_workgroup_size: 512
    .name:           _Z8mega_fwd4Args
    .private_segment_fixed_size: 0
    .sgpr_count:     106
    .sgpr_spill_count: 31
    .symbol:         _Z8mega_fwd4Args.kd
    .uniform_work_group_size: 1
    .uses_dynamic_stack: false
    .vgpr_count:     256
    .vgpr_spill_count: 0
    .wavefront_size: 64
